# out-GEMM residual/norm epilogue rewritten: batched loads, DPP row exchange so f32 loads/stores cover full 128-B lines, row-ssq atomics batched per 4 rows
# speedup vs baseline: 1.0199x; 1.0052x over previous
; #define EPI_COL(u) (EPI_CB(u) + 8 * fq)
; DI u32x4 pack8(const float* v) { u32x4 w; w.x = pk2(v[0], v[1]); w.y = pk2(v[2], v[3]); w.z = pk2(v[4], v[5]); w.w = pk2(v[6], v[7]); return w; }
;     DI void operator()(const Acc& acc, const Unit& u, int wr, int wc, int fr, int fq) const {
; #pragma unroll
;         for (int ai = 0; ai < 2; ++ai)
; #pragma unroll
;             for (int m = 0; m < 4; ++m) {
;                 const int row = EPI_ROW(u); float part = 0.f;
; #pragma unroll
;                 for (int bj = 0; bj < 2; ++bj) {
;                     const int col = EPI_COL(u);
;                     const float* rp = res + (size_t)row * 1024 + col; float* op = out + (size_t)row * 1024 + col;
;                     const f32x4 o0 = *(const f32x4*)rp + acc[ai][bj][m][0], o1 = *(const f32x4*)(rp + 4) + acc[ai][bj][m][1];
;                     *(f32x4*)op = o0; *(f32x4*)(op + 4) = o1;
;                     part += o0[0] * o0[0] + o0[1] * o0[1] + o0[2] * o0[2] + o0[3] * o0[3] + o1[0] * o1[0] + o1[1] * o1[1] + o1[2] * o1[2] + o1[3] * o1[3];
;                     const float v[8] = {o0[0], o0[1], o0[2], o0[3], o1[0], o1[1], o1[2], o1[3]};
;                     *(u32x4*)(xb + (size_t)row * 1024 + col) = pack8(v);
;                 }
;                 part += __shfl_xor(part, 16); part += __shfl_xor(part, 32);
;                 if (fq == 0) atomicAdd(rss + row, part);
;             }
;     }
.LBB0_1299:
	v_and_b32_e32 v242, 64, v233
	v_xor_b32_e32 v241, 16, v233
	v_add_u32_e32 v243, 64, v242
	v_cmp_lt_i32_e32 vcc, v241, v243
	s_lshl_b32 s2, s54, 8
	v_cndmask_b32_e32 v241, v233, v241, vcc
	s_add_i32 s2, s2, s86
	v_lshlrev_b32_e32 v242, 2, v241
	v_xor_b32_e32 v241, 32, v233
	v_cmp_lt_i32_e32 vcc, v241, v243
	v_add_u32_e32 v240, s2, v146
	s_lshl_b32 s2, s50, 8
	s_or_b32 s2, s2, s87
	v_cndmask_b32_e32 v241, v233, v241, vcc
	v_lshlrev_b32_e32 v243, 2, v241
	v_lshl_add_u32 v241, v147, 3, s2
	v_cmp_eq_u32_e32 vcc, 0, v147
	v_lshlrev_b32_e32 v186, 12, v240
	v_lshl_add_u32 v186, v241, 2, v186
	v_lshrrev_b32_e32 v187, 1, v186
	v_and_b32_e32 v230, 8, v233
	v_mul_u32_u24_e32 v230, 0xffe, v230
	v_sub_u32_e32 v186, v186, v230
	v_add_u32_e32 v230, 0x0, v186
	v_add_u32_e32 v231, 0x8000, v186
	global_load_dwordx4 v[138:141], v230, s[20:21]
	global_load_dwordx4 v[142:145], v231, s[20:21]
	global_load_dwordx4 v[150:153], v230, s[20:21] offset:512
	global_load_dwordx4 v[154:157], v231, s[20:21] offset:512
	v_add_u32_e32 v230, 0x10000, v186
	v_add_u32_e32 v231, 0x18000, v186
	global_load_dwordx4 v[158:161], v230, s[20:21]
	global_load_dwordx4 v[162:165], v231, s[20:21]
	global_load_dwordx4 v[166:169], v230, s[20:21] offset:512
	global_load_dwordx4 v[170:173], v231, s[20:21] offset:512
	v_add_u32_e32 v230, 0x20000, v186
	v_add_u32_e32 v231, 0x28000, v186
	global_load_dwordx4 v[174:177], v230, s[20:21]
	global_load_dwordx4 v[178:181], v231, s[20:21]
	global_load_dwordx4 v[182:185], v230, s[20:21] offset:512
	global_load_dwordx4 v[210:213], v231, s[20:21] offset:512
	v_add_u32_e32 v230, 0x30000, v186
	v_add_u32_e32 v231, 0x38000, v186
	global_load_dwordx4 v[214:217], v230, s[20:21]
	global_load_dwordx4 v[218:221], v231, s[20:21]
	global_load_dwordx4 v[222:225], v230, s[20:21] offset:512
	global_load_dwordx4 v[226:229], v231, s[20:21] offset:512
	s_waitcnt vmcnt(0)
	v_mov_b32_e32 v244, v138
	v_mov_b32_e32 v245, v139
	v_mov_b32_e32 v246, v140
	v_mov_b32_e32 v247, v141
	v_mov_b32_dpp v138, v142 row_ror:8 row_mask:0xf bank_mask:0xc
	v_mov_b32_dpp v139, v143 row_ror:8 row_mask:0xf bank_mask:0xc
	v_mov_b32_dpp v140, v144 row_ror:8 row_mask:0xf bank_mask:0xc
	v_mov_b32_dpp v141, v145 row_ror:8 row_mask:0xf bank_mask:0xc
	v_mov_b32_dpp v142, v244 row_ror:8 row_mask:0xf bank_mask:0x3
	v_mov_b32_dpp v143, v245 row_ror:8 row_mask:0xf bank_mask:0x3
	v_mov_b32_dpp v144, v246 row_ror:8 row_mask:0xf bank_mask:0x3
	v_mov_b32_dpp v145, v247 row_ror:8 row_mask:0xf bank_mask:0x3
	v_pk_add_f32 v[124:125], v[124:125], v[138:139]
	v_pk_add_f32 v[126:127], v[126:127], v[140:141]
	v_pk_add_f32 v[120:121], v[120:121], v[142:143]
	v_pk_add_f32 v[122:123], v[122:123], v[144:145]
	v_mul_f32_e32 v235, v124, v124
	v_fmac_f32_e32 v235, v125, v125
	v_fmac_f32_e32 v235, v126, v126
	v_fmac_f32_e32 v235, v127, v127
	v_fmac_f32_e32 v235, v120, v120
	v_fmac_f32_e32 v235, v121, v121
	v_fmac_f32_e32 v235, v122, v122
	v_fmac_f32_e32 v235, v123, v123
	v_cvt_pk_bf16_f32 v138, v124, v125
	v_cvt_pk_bf16_f32 v139, v126, v127
	v_cvt_pk_bf16_f32 v140, v120, v121
	v_cvt_pk_bf16_f32 v141, v122, v123
	v_add_u32_e32 v234, 0x0, v187
	global_store_dwordx4 v234, v[138:141], s[26:27]
	v_mov_b32_e32 v244, v120
	v_mov_b32_e32 v245, v121
	v_mov_b32_e32 v246, v122
	v_mov_b32_e32 v247, v123
	v_mov_b32_dpp v120, v124 row_ror:8 row_mask:0xf bank_mask:0x3
	v_mov_b32_dpp v121, v125 row_ror:8 row_mask:0xf bank_mask:0x3
	v_mov_b32_dpp v122, v126 row_ror:8 row_mask:0xf bank_mask:0x3
	v_mov_b32_dpp v123, v127 row_ror:8 row_mask:0xf bank_mask:0x3
	v_mov_b32_dpp v124, v244 row_ror:8 row_mask:0xf bank_mask:0xc
	v_mov_b32_dpp v125, v245 row_ror:8 row_mask:0xf bank_mask:0xc
	v_mov_b32_dpp v126, v246 row_ror:8 row_mask:0xf bank_mask:0xc
	v_mov_b32_dpp v127, v247 row_ror:8 row_mask:0xf bank_mask:0xc
	v_add_u32_e32 v230, 0x0, v186
	v_add_u32_e32 v231, 0x8000, v186
	global_store_dwordx4 v230, v[124:127], s[24:25]
	global_store_dwordx4 v231, v[120:123], s[24:25]
	v_mov_b32_e32 v244, v150
	v_mov_b32_e32 v245, v151
	v_mov_b32_e32 v246, v152
	v_mov_b32_e32 v247, v153
	v_mov_b32_dpp v150, v154 row_ror:8 row_mask:0xf bank_mask:0xc
	v_mov_b32_dpp v151, v155 row_ror:8 row_mask:0xf bank_mask:0xc
	v_mov_b32_dpp v152, v156 row_ror:8 row_mask:0xf bank_mask:0xc
	v_mov_b32_dpp v153, v157 row_ror:8 row_mask:0xf bank_mask:0xc
	v_mov_b32_dpp v154, v244 row_ror:8 row_mask:0xf bank_mask:0x3
	v_mov_b32_dpp v155, v245 row_ror:8 row_mask:0xf bank_mask:0x3
	v_mov_b32_dpp v156, v246 row_ror:8 row_mask:0xf bank_mask:0x3
	v_mov_b32_dpp v157, v247 row_ror:8 row_mask:0xf bank_mask:0x3
	v_pk_add_f32 v[116:117], v[116:117], v[150:151]
	v_pk_add_f32 v[118:119], v[118:119], v[152:153]
	v_pk_add_f32 v[112:113], v[112:113], v[154:155]
	v_pk_add_f32 v[114:115], v[114:115], v[156:157]
	v_fmac_f32_e32 v235, v116, v116
	v_fmac_f32_e32 v235, v117, v117
	v_fmac_f32_e32 v235, v118, v118
	v_fmac_f32_e32 v235, v119, v119
	v_fmac_f32_e32 v235, v112, v112
	v_fmac_f32_e32 v235, v113, v113
	v_fmac_f32_e32 v235, v114, v114
	v_fmac_f32_e32 v235, v115, v115
	v_cvt_pk_bf16_f32 v150, v116, v117
	v_cvt_pk_bf16_f32 v151, v118, v119
	v_cvt_pk_bf16_f32 v152, v112, v113
	v_cvt_pk_bf16_f32 v153, v114, v115
	global_store_dwordx4 v234, v[150:153], s[26:27] offset:256
	v_mov_b32_e32 v244, v112
	v_mov_b32_e32 v245, v113
	v_mov_b32_e32 v246, v114
	v_mov_b32_e32 v247, v115
	v_mov_b32_dpp v112, v116 row_ror:8 row_mask:0xf bank_mask:0x3
	v_mov_b32_dpp v113, v117 row_ror:8 row_mask:0xf bank_mask:0x3
	v_mov_b32_dpp v114, v118 row_ror:8 row_mask:0xf bank_mask:0x3
	v_mov_b32_dpp v115, v119 row_ror:8 row_mask:0xf bank_mask:0x3
	v_mov_b32_dpp v116, v244 row_ror:8 row_mask:0xf bank_mask:0xc
; #define EPI_COL(u) (EPI_CB(u) + 8 * fq)
; DI u32x4 pack8(const float* v) { u32x4 w; w.x = pk2(v[0], v[1]); w.y = pk2(v[2], v[3]); w.z = pk2(v[4], v[5]); w.w = pk2(v[6], v[7]); return w; }
;     DI void operator()(const Acc& acc, const Unit& u, int wr, int wc, int fr, int fq) const {
;     ...
;                 const int row = EPI_ROW(u); float part = 0.f;
; #pragma unroll
;                 for (int bj = 0; bj < 2; ++bj) {
;                     const int col = EPI_COL(u);
;                     const float* rp = res + (size_t)row * 1024 + col; float* op = out + (size_t)row * 1024 + col;
;                     const f32x4 o0 = *(const f32x4*)rp + acc[ai][bj][m][0], o1 = *(const f32x4*)(rp + 4) + acc[ai][bj][m][1];
;                     *(f32x4*)op = o0; *(f32x4*)(op + 4) = o1;
;                     part += o0[0] * o0[0] + o0[1] * o0[1] + o0[2] * o0[2] + o0[3] * o0[3] + o1[0] * o1[0] + o1[1] * o1[1] + o1[2] * o1[2] + o1[3] * o1[3];
;                     const float v[8] = {o0[0], o0[1], o0[2], o0[3], o1[0], o1[1], o1[2], o1[3]};
;                     *(u32x4*)(xb + (size_t)row * 1024 + col) = pack8(v);
;                 }
	v_mov_b32_dpp v117, v245 row_ror:8 row_mask:0xf bank_mask:0xc
	v_mov_b32_dpp v118, v246 row_ror:8 row_mask:0xf bank_mask:0xc
	v_mov_b32_dpp v119, v247 row_ror:8 row_mask:0xf bank_mask:0xc
	global_store_dwordx4 v230, v[116:119], s[24:25] offset:512
	global_store_dwordx4 v231, v[112:115], s[24:25] offset:512
	v_mov_b32_e32 v244, v158
	v_mov_b32_e32 v245, v159
	v_mov_b32_e32 v246, v160
	v_mov_b32_e32 v247, v161
	v_mov_b32_dpp v158, v162 row_ror:8 row_mask:0xf bank_mask:0xc
	v_mov_b32_dpp v159, v163 row_ror:8 row_mask:0xf bank_mask:0xc
	v_mov_b32_dpp v160, v164 row_ror:8 row_mask:0xf bank_mask:0xc
	v_mov_b32_dpp v161, v165 row_ror:8 row_mask:0xf bank_mask:0xc
	v_mov_b32_dpp v162, v244 row_ror:8 row_mask:0xf bank_mask:0x3
	v_mov_b32_dpp v163, v245 row_ror:8 row_mask:0xf bank_mask:0x3
	v_mov_b32_dpp v164, v246 row_ror:8 row_mask:0xf bank_mask:0x3
	v_mov_b32_dpp v165, v247 row_ror:8 row_mask:0xf bank_mask:0x3
	v_pk_add_f32 v[108:109], v[108:109], v[158:159]
	v_pk_add_f32 v[110:111], v[110:111], v[160:161]
	v_pk_add_f32 v[104:105], v[104:105], v[162:163]
	v_pk_add_f32 v[106:107], v[106:107], v[164:165]
	v_mul_f32_e32 v236, v108, v108
	v_fmac_f32_e32 v236, v109, v109
	v_fmac_f32_e32 v236, v110, v110
	v_fmac_f32_e32 v236, v111, v111
	v_fmac_f32_e32 v236, v104, v104
	v_fmac_f32_e32 v236, v105, v105
	v_fmac_f32_e32 v236, v106, v106
	v_fmac_f32_e32 v236, v107, v107
	v_cvt_pk_bf16_f32 v158, v108, v109
	v_cvt_pk_bf16_f32 v159, v110, v111
	v_cvt_pk_bf16_f32 v160, v104, v105
	v_cvt_pk_bf16_f32 v161, v106, v107
	v_add_u32_e32 v234, 0x8000, v187
	global_store_dwordx4 v234, v[158:161], s[26:27]
	v_mov_b32_e32 v244, v104
	v_mov_b32_e32 v245, v105
	v_mov_b32_e32 v246, v106
	v_mov_b32_e32 v247, v107
	v_mov_b32_dpp v104, v108 row_ror:8 row_mask:0xf bank_mask:0x3
	v_mov_b32_dpp v105, v109 row_ror:8 row_mask:0xf bank_mask:0x3
	v_mov_b32_dpp v106, v110 row_ror:8 row_mask:0xf bank_mask:0x3
	v_mov_b32_dpp v107, v111 row_ror:8 row_mask:0xf bank_mask:0x3
	v_mov_b32_dpp v108, v244 row_ror:8 row_mask:0xf bank_mask:0xc
	v_mov_b32_dpp v109, v245 row_ror:8 row_mask:0xf bank_mask:0xc
	v_mov_b32_dpp v110, v246 row_ror:8 row_mask:0xf bank_mask:0xc
	v_mov_b32_dpp v111, v247 row_ror:8 row_mask:0xf bank_mask:0xc
	v_add_u32_e32 v230, 0x10000, v186
	v_add_u32_e32 v231, 0x18000, v186
	global_store_dwordx4 v230, v[108:111], s[24:25]
	global_store_dwordx4 v231, v[104:107], s[24:25]
	v_mov_b32_e32 v244, v166
	v_mov_b32_e32 v245, v167
	v_mov_b32_e32 v246, v168
	v_mov_b32_e32 v247, v169
	v_mov_b32_dpp v166, v170 row_ror:8 row_mask:0xf bank_mask:0xc
	v_mov_b32_dpp v167, v171 row_ror:8 row_mask:0xf bank_mask:0xc
	v_mov_b32_dpp v168, v172 row_ror:8 row_mask:0xf bank_mask:0xc
	v_mov_b32_dpp v169, v173 row_ror:8 row_mask:0xf bank_mask:0xc
	v_mov_b32_dpp v170, v244 row_ror:8 row_mask:0xf bank_mask:0x3
	v_mov_b32_dpp v171, v245 row_ror:8 row_mask:0xf bank_mask:0x3
	v_mov_b32_dpp v172, v246 row_ror:8 row_mask:0xf bank_mask:0x3
	v_mov_b32_dpp v173, v247 row_ror:8 row_mask:0xf bank_mask:0x3
	v_pk_add_f32 v[100:101], v[100:101], v[166:167]
	v_pk_add_f32 v[102:103], v[102:103], v[168:169]
	v_pk_add_f32 v[96:97], v[96:97], v[170:171]
	v_pk_add_f32 v[98:99], v[98:99], v[172:173]
	v_fmac_f32_e32 v236, v100, v100
	v_fmac_f32_e32 v236, v101, v101
	v_fmac_f32_e32 v236, v102, v102
	v_fmac_f32_e32 v236, v103, v103
	v_fmac_f32_e32 v236, v96, v96
	v_fmac_f32_e32 v236, v97, v97
	v_fmac_f32_e32 v236, v98, v98
	v_fmac_f32_e32 v236, v99, v99
	v_cvt_pk_bf16_f32 v166, v100, v101
	v_cvt_pk_bf16_f32 v167, v102, v103
	v_cvt_pk_bf16_f32 v168, v96, v97
	v_cvt_pk_bf16_f32 v169, v98, v99
	global_store_dwordx4 v234, v[166:169], s[26:27] offset:256
	v_mov_b32_e32 v244, v96
	v_mov_b32_e32 v245, v97
	v_mov_b32_e32 v246, v98
	v_mov_b32_e32 v247, v99
	v_mov_b32_dpp v96, v100 row_ror:8 row_mask:0xf bank_mask:0x3
	v_mov_b32_dpp v97, v101 row_ror:8 row_mask:0xf bank_mask:0x3
	v_mov_b32_dpp v98, v102 row_ror:8 row_mask:0xf bank_mask:0x3
	v_mov_b32_dpp v99, v103 row_ror:8 row_mask:0xf bank_mask:0x3
	v_mov_b32_dpp v100, v244 row_ror:8 row_mask:0xf bank_mask:0xc
	v_mov_b32_dpp v101, v245 row_ror:8 row_mask:0xf bank_mask:0xc
	v_mov_b32_dpp v102, v246 row_ror:8 row_mask:0xf bank_mask:0xc
	v_mov_b32_dpp v103, v247 row_ror:8 row_mask:0xf bank_mask:0xc
	global_store_dwordx4 v230, v[100:103], s[24:25] offset:512
	global_store_dwordx4 v231, v[96:99], s[24:25] offset:512
	v_mov_b32_e32 v244, v174
	v_mov_b32_e32 v245, v175
	v_mov_b32_e32 v246, v176
	v_mov_b32_e32 v247, v177
	v_mov_b32_dpp v174, v178 row_ror:8 row_mask:0xf bank_mask:0xc
	v_mov_b32_dpp v175, v179 row_ror:8 row_mask:0xf bank_mask:0xc
	v_mov_b32_dpp v176, v180 row_ror:8 row_mask:0xf bank_mask:0xc
	v_mov_b32_dpp v177, v181 row_ror:8 row_mask:0xf bank_mask:0xc
	v_mov_b32_dpp v178, v244 row_ror:8 row_mask:0xf bank_mask:0x3
	v_mov_b32_dpp v179, v245 row_ror:8 row_mask:0xf bank_mask:0x3
	v_mov_b32_dpp v180, v246 row_ror:8 row_mask:0xf bank_mask:0x3
	v_mov_b32_dpp v181, v247 row_ror:8 row_mask:0xf bank_mask:0x3
	v_pk_add_f32 v[92:93], v[92:93], v[174:175]
	v_pk_add_f32 v[94:95], v[94:95], v[176:177]
	v_pk_add_f32 v[88:89], v[88:89], v[178:179]
	v_pk_add_f32 v[90:91], v[90:91], v[180:181]
	v_mul_f32_e32 v237, v92, v92
	v_fmac_f32_e32 v237, v93, v93
	v_fmac_f32_e32 v237, v94, v94
	v_fmac_f32_e32 v237, v95, v95
	v_fmac_f32_e32 v237, v88, v88
	v_fmac_f32_e32 v237, v89, v89
	v_fmac_f32_e32 v237, v90, v90
	v_fmac_f32_e32 v237, v91, v91
	v_cvt_pk_bf16_f32 v174, v92, v93
	v_cvt_pk_bf16_f32 v175, v94, v95
	v_cvt_pk_bf16_f32 v176, v88, v89
	v_cvt_pk_bf16_f32 v177, v90, v91
	v_add_u32_e32 v234, 0x10000, v187
	global_store_dwordx4 v234, v[174:177], s[26:27]
	v_mov_b32_e32 v244, v88
; #define EPI_COL(u) (EPI_CB(u) + 8 * fq)
; DI u32x4 pack8(const float* v) { u32x4 w; w.x = pk2(v[0], v[1]); w.y = pk2(v[2], v[3]); w.z = pk2(v[4], v[5]); w.w = pk2(v[6], v[7]); return w; }
;     DI void operator()(const Acc& acc, const Unit& u, int wr, int wc, int fr, int fq) const {
;     ...
;                 const int row = EPI_ROW(u); float part = 0.f;
; #pragma unroll
;                 for (int bj = 0; bj < 2; ++bj) {
;                     const int col = EPI_COL(u);
;                     const float* rp = res + (size_t)row * 1024 + col; float* op = out + (size_t)row * 1024 + col;
;                     const f32x4 o0 = *(const f32x4*)rp + acc[ai][bj][m][0], o1 = *(const f32x4*)(rp + 4) + acc[ai][bj][m][1];
;                     *(f32x4*)op = o0; *(f32x4*)(op + 4) = o1;
;                     part += o0[0] * o0[0] + o0[1] * o0[1] + o0[2] * o0[2] + o0[3] * o0[3] + o1[0] * o1[0] + o1[1] * o1[1] + o1[2] * o1[2] + o1[3] * o1[3];
;                     const float v[8] = {o0[0], o0[1], o0[2], o0[3], o1[0], o1[1], o1[2], o1[3]};
;                     *(u32x4*)(xb + (size_t)row * 1024 + col) = pack8(v);
;                 }
;                 part += __shfl_xor(part, 16); part += __shfl_xor(part, 32);
	v_mov_b32_e32 v245, v89
	v_mov_b32_e32 v246, v90
	v_mov_b32_e32 v247, v91
	v_mov_b32_dpp v88, v92 row_ror:8 row_mask:0xf bank_mask:0x3
	v_mov_b32_dpp v89, v93 row_ror:8 row_mask:0xf bank_mask:0x3
	v_mov_b32_dpp v90, v94 row_ror:8 row_mask:0xf bank_mask:0x3
	v_mov_b32_dpp v91, v95 row_ror:8 row_mask:0xf bank_mask:0x3
	v_mov_b32_dpp v92, v244 row_ror:8 row_mask:0xf bank_mask:0xc
	v_mov_b32_dpp v93, v245 row_ror:8 row_mask:0xf bank_mask:0xc
	v_mov_b32_dpp v94, v246 row_ror:8 row_mask:0xf bank_mask:0xc
	v_mov_b32_dpp v95, v247 row_ror:8 row_mask:0xf bank_mask:0xc
	v_add_u32_e32 v230, 0x20000, v186
	v_add_u32_e32 v231, 0x28000, v186
	global_store_dwordx4 v230, v[92:95], s[24:25]
	global_store_dwordx4 v231, v[88:91], s[24:25]
	v_mov_b32_e32 v244, v182
	v_mov_b32_e32 v245, v183
	v_mov_b32_e32 v246, v184
	v_mov_b32_e32 v247, v185
	v_mov_b32_dpp v182, v210 row_ror:8 row_mask:0xf bank_mask:0xc
	v_mov_b32_dpp v183, v211 row_ror:8 row_mask:0xf bank_mask:0xc
	v_mov_b32_dpp v184, v212 row_ror:8 row_mask:0xf bank_mask:0xc
	v_mov_b32_dpp v185, v213 row_ror:8 row_mask:0xf bank_mask:0xc
	v_mov_b32_dpp v210, v244 row_ror:8 row_mask:0xf bank_mask:0x3
	v_mov_b32_dpp v211, v245 row_ror:8 row_mask:0xf bank_mask:0x3
	v_mov_b32_dpp v212, v246 row_ror:8 row_mask:0xf bank_mask:0x3
	v_mov_b32_dpp v213, v247 row_ror:8 row_mask:0xf bank_mask:0x3
	v_pk_add_f32 v[84:85], v[84:85], v[182:183]
	v_pk_add_f32 v[86:87], v[86:87], v[184:185]
	v_pk_add_f32 v[80:81], v[80:81], v[210:211]
	v_pk_add_f32 v[82:83], v[82:83], v[212:213]
	v_fmac_f32_e32 v237, v84, v84
	v_fmac_f32_e32 v237, v85, v85
	v_fmac_f32_e32 v237, v86, v86
	v_fmac_f32_e32 v237, v87, v87
	v_fmac_f32_e32 v237, v80, v80
	v_fmac_f32_e32 v237, v81, v81
	v_fmac_f32_e32 v237, v82, v82
	v_fmac_f32_e32 v237, v83, v83
	v_cvt_pk_bf16_f32 v182, v84, v85
	v_cvt_pk_bf16_f32 v183, v86, v87
	v_cvt_pk_bf16_f32 v184, v80, v81
	v_cvt_pk_bf16_f32 v185, v82, v83
	global_store_dwordx4 v234, v[182:185], s[26:27] offset:256
	v_mov_b32_e32 v244, v80
	v_mov_b32_e32 v245, v81
	v_mov_b32_e32 v246, v82
	v_mov_b32_e32 v247, v83
	v_mov_b32_dpp v80, v84 row_ror:8 row_mask:0xf bank_mask:0x3
	v_mov_b32_dpp v81, v85 row_ror:8 row_mask:0xf bank_mask:0x3
	v_mov_b32_dpp v82, v86 row_ror:8 row_mask:0xf bank_mask:0x3
	v_mov_b32_dpp v83, v87 row_ror:8 row_mask:0xf bank_mask:0x3
	v_mov_b32_dpp v84, v244 row_ror:8 row_mask:0xf bank_mask:0xc
	v_mov_b32_dpp v85, v245 row_ror:8 row_mask:0xf bank_mask:0xc
	v_mov_b32_dpp v86, v246 row_ror:8 row_mask:0xf bank_mask:0xc
	v_mov_b32_dpp v87, v247 row_ror:8 row_mask:0xf bank_mask:0xc
	global_store_dwordx4 v230, v[84:87], s[24:25] offset:512
	global_store_dwordx4 v231, v[80:83], s[24:25] offset:512
	v_mov_b32_e32 v244, v214
	v_mov_b32_e32 v245, v215
	v_mov_b32_e32 v246, v216
	v_mov_b32_e32 v247, v217
	v_mov_b32_dpp v214, v218 row_ror:8 row_mask:0xf bank_mask:0xc
	v_mov_b32_dpp v215, v219 row_ror:8 row_mask:0xf bank_mask:0xc
	v_mov_b32_dpp v216, v220 row_ror:8 row_mask:0xf bank_mask:0xc
	v_mov_b32_dpp v217, v221 row_ror:8 row_mask:0xf bank_mask:0xc
	v_mov_b32_dpp v218, v244 row_ror:8 row_mask:0xf bank_mask:0x3
	v_mov_b32_dpp v219, v245 row_ror:8 row_mask:0xf bank_mask:0x3
	v_mov_b32_dpp v220, v246 row_ror:8 row_mask:0xf bank_mask:0x3
	v_mov_b32_dpp v221, v247 row_ror:8 row_mask:0xf bank_mask:0x3
	v_pk_add_f32 v[76:77], v[76:77], v[214:215]
	v_pk_add_f32 v[78:79], v[78:79], v[216:217]
	v_pk_add_f32 v[72:73], v[72:73], v[218:219]
	v_pk_add_f32 v[74:75], v[74:75], v[220:221]
	v_mul_f32_e32 v248, v76, v76
	v_fmac_f32_e32 v248, v77, v77
	v_fmac_f32_e32 v248, v78, v78
	v_fmac_f32_e32 v248, v79, v79
	v_fmac_f32_e32 v248, v72, v72
	v_fmac_f32_e32 v248, v73, v73
	v_fmac_f32_e32 v248, v74, v74
	v_fmac_f32_e32 v248, v75, v75
	v_cvt_pk_bf16_f32 v214, v76, v77
	v_cvt_pk_bf16_f32 v215, v78, v79
	v_cvt_pk_bf16_f32 v216, v72, v73
	v_cvt_pk_bf16_f32 v217, v74, v75
	v_add_u32_e32 v234, 0x18000, v187
	global_store_dwordx4 v234, v[214:217], s[26:27]
	v_mov_b32_e32 v244, v72
	v_mov_b32_e32 v245, v73
	v_mov_b32_e32 v246, v74
	v_mov_b32_e32 v247, v75
	v_mov_b32_dpp v72, v76 row_ror:8 row_mask:0xf bank_mask:0x3
	v_mov_b32_dpp v73, v77 row_ror:8 row_mask:0xf bank_mask:0x3
	v_mov_b32_dpp v74, v78 row_ror:8 row_mask:0xf bank_mask:0x3
	v_mov_b32_dpp v75, v79 row_ror:8 row_mask:0xf bank_mask:0x3
	v_mov_b32_dpp v76, v244 row_ror:8 row_mask:0xf bank_mask:0xc
	v_mov_b32_dpp v77, v245 row_ror:8 row_mask:0xf bank_mask:0xc
	v_mov_b32_dpp v78, v246 row_ror:8 row_mask:0xf bank_mask:0xc
	v_mov_b32_dpp v79, v247 row_ror:8 row_mask:0xf bank_mask:0xc
	v_add_u32_e32 v230, 0x30000, v186
	v_add_u32_e32 v231, 0x38000, v186
	global_store_dwordx4 v230, v[76:79], s[24:25]
	global_store_dwordx4 v231, v[72:75], s[24:25]
	v_mov_b32_e32 v244, v222
	v_mov_b32_e32 v245, v223
	v_mov_b32_e32 v246, v224
	v_mov_b32_e32 v247, v225
	v_mov_b32_dpp v222, v226 row_ror:8 row_mask:0xf bank_mask:0xc
	v_mov_b32_dpp v223, v227 row_ror:8 row_mask:0xf bank_mask:0xc
	v_mov_b32_dpp v224, v228 row_ror:8 row_mask:0xf bank_mask:0xc
	v_mov_b32_dpp v225, v229 row_ror:8 row_mask:0xf bank_mask:0xc
	v_mov_b32_dpp v226, v244 row_ror:8 row_mask:0xf bank_mask:0x3
	v_mov_b32_dpp v227, v245 row_ror:8 row_mask:0xf bank_mask:0x3
	v_mov_b32_dpp v228, v246 row_ror:8 row_mask:0xf bank_mask:0x3
	v_mov_b32_dpp v229, v247 row_ror:8 row_mask:0xf bank_mask:0x3
	v_pk_add_f32 v[68:69], v[68:69], v[222:223]
	v_pk_add_f32 v[70:71], v[70:71], v[224:225]
	v_pk_add_f32 v[64:65], v[64:65], v[226:227]
	v_pk_add_f32 v[66:67], v[66:67], v[228:229]
	v_fmac_f32_e32 v248, v68, v68
	v_fmac_f32_e32 v248, v69, v69
	v_fmac_f32_e32 v248, v70, v70
	v_fmac_f32_e32 v248, v71, v71
	v_fmac_f32_e32 v248, v64, v64
	v_fmac_f32_e32 v248, v65, v65
	v_fmac_f32_e32 v248, v66, v66
	v_fmac_f32_e32 v248, v67, v67
	v_cvt_pk_bf16_f32 v222, v68, v69
	v_cvt_pk_bf16_f32 v223, v70, v71
	v_cvt_pk_bf16_f32 v224, v64, v65
	v_cvt_pk_bf16_f32 v225, v66, v67
	global_store_dwordx4 v234, v[222:225], s[26:27] offset:256
	v_mov_b32_e32 v244, v64
	v_mov_b32_e32 v245, v65
	v_mov_b32_e32 v246, v66
	v_mov_b32_e32 v247, v67
	v_mov_b32_dpp v64, v68 row_ror:8 row_mask:0xf bank_mask:0x3
	v_mov_b32_dpp v65, v69 row_ror:8 row_mask:0xf bank_mask:0x3
	v_mov_b32_dpp v66, v70 row_ror:8 row_mask:0xf bank_mask:0x3
	v_mov_b32_dpp v67, v71 row_ror:8 row_mask:0xf bank_mask:0x3
	v_mov_b32_dpp v68, v244 row_ror:8 row_mask:0xf bank_mask:0xc
	v_mov_b32_dpp v69, v245 row_ror:8 row_mask:0xf bank_mask:0xc
	v_mov_b32_dpp v70, v246 row_ror:8 row_mask:0xf bank_mask:0xc
	v_mov_b32_dpp v71, v247 row_ror:8 row_mask:0xf bank_mask:0xc
	global_store_dwordx4 v230, v[68:71], s[24:25] offset:512
	global_store_dwordx4 v231, v[64:67], s[24:25] offset:512
	ds_bpermute_b32 v138, v242, v235
	ds_bpermute_b32 v142, v242, v236
	ds_bpermute_b32 v150, v242, v237
	ds_bpermute_b32 v154, v242, v248
	s_waitcnt lgkmcnt(0)
; #define EPI_COL(u) (EPI_CB(u) + 8 * fq)
; DI u32x4 pack8(const float* v) { u32x4 w; w.x = pk2(v[0], v[1]); w.y = pk2(v[2], v[3]); w.z = pk2(v[4], v[5]); w.w = pk2(v[6], v[7]); return w; }
;     DI void operator()(const Acc& acc, const Unit& u, int wr, int wc, int fr, int fq) const {
;     ...
;                 const int row = EPI_ROW(u); float part = 0.f;
; #pragma unroll
;                 for (int bj = 0; bj < 2; ++bj) {
;                     const int col = EPI_COL(u);
;                     const float* rp = res + (size_t)row * 1024 + col; float* op = out + (size_t)row * 1024 + col;
;                     const f32x4 o0 = *(const f32x4*)rp + acc[ai][bj][m][0], o1 = *(const f32x4*)(rp + 4) + acc[ai][bj][m][1];
;                     *(f32x4*)op = o0; *(f32x4*)(op + 4) = o1;
;                     part += o0[0] * o0[0] + o0[1] * o0[1] + o0[2] * o0[2] + o0[3] * o0[3] + o1[0] * o1[0] + o1[1] * o1[1] + o1[2] * o1[2] + o1[3] * o1[3];
;                     const float v[8] = {o0[0], o0[1], o0[2], o0[3], o1[0], o1[1], o1[2], o1[3]};
;                     *(u32x4*)(xb + (size_t)row * 1024 + col) = pack8(v);
;                 }
;                 part += __shfl_xor(part, 16); part += __shfl_xor(part, 32);
;                 if (fq == 0) atomicAdd(rss + row, part);
	v_add_f32_e32 v235, v235, v138
	v_add_f32_e32 v236, v236, v142
	v_add_f32_e32 v237, v237, v150
	v_add_f32_e32 v248, v248, v154
	ds_bpermute_b32 v138, v243, v235
	ds_bpermute_b32 v142, v243, v236
	ds_bpermute_b32 v150, v243, v237
	ds_bpermute_b32 v154, v243, v248
	s_waitcnt lgkmcnt(0)
	v_add_f32_e32 v235, v235, v138
	v_add_f32_e32 v236, v236, v142
	v_add_f32_e32 v237, v237, v150
	v_add_f32_e32 v248, v248, v154
	s_and_saveexec_b64 s[6:7], vcc
	v_lshlrev_b32_e32 v234, 2, v240
	global_atomic_add_f32 v234, v235, s[38:39] offset:0
	global_atomic_add_f32 v234, v236, s[38:39] offset:64
	global_atomic_add_f32 v234, v237, s[38:39] offset:128
	global_atomic_add_f32 v234, v248, s[38:39] offset:192
	s_or_b64 exec, exec, s[6:7]
	v_add_u32_e32 v230, 0x80000, v186
	v_add_u32_e32 v231, 0x88000, v186
	global_load_dwordx4 v[138:141], v230, s[20:21]
	global_load_dwordx4 v[142:145], v231, s[20:21]
	global_load_dwordx4 v[150:153], v230, s[20:21] offset:512
	global_load_dwordx4 v[154:157], v231, s[20:21] offset:512
	v_add_u32_e32 v230, 0x90000, v186
	v_add_u32_e32 v231, 0x98000, v186
	global_load_dwordx4 v[158:161], v230, s[20:21]
	global_load_dwordx4 v[162:165], v231, s[20:21]
	global_load_dwordx4 v[166:169], v230, s[20:21] offset:512
	global_load_dwordx4 v[170:173], v231, s[20:21] offset:512
	v_add_u32_e32 v230, 0xa0000, v186
	v_add_u32_e32 v231, 0xa8000, v186
	global_load_dwordx4 v[174:177], v230, s[20:21]
	global_load_dwordx4 v[178:181], v231, s[20:21]
	global_load_dwordx4 v[182:185], v230, s[20:21] offset:512
	global_load_dwordx4 v[210:213], v231, s[20:21] offset:512
	v_add_u32_e32 v230, 0xb0000, v186
	v_add_u32_e32 v231, 0xb8000, v186
	global_load_dwordx4 v[214:217], v230, s[20:21]
	global_load_dwordx4 v[218:221], v231, s[20:21]
	global_load_dwordx4 v[222:225], v230, s[20:21] offset:512
	global_load_dwordx4 v[226:229], v231, s[20:21] offset:512
	s_waitcnt vmcnt(0)
	v_mov_b32_e32 v244, v138
	v_mov_b32_e32 v245, v139
	v_mov_b32_e32 v246, v140
	v_mov_b32_e32 v247, v141
	v_mov_b32_dpp v138, v142 row_ror:8 row_mask:0xf bank_mask:0xc
	v_mov_b32_dpp v139, v143 row_ror:8 row_mask:0xf bank_mask:0xc
	v_mov_b32_dpp v140, v144 row_ror:8 row_mask:0xf bank_mask:0xc
	v_mov_b32_dpp v141, v145 row_ror:8 row_mask:0xf bank_mask:0xc
	v_mov_b32_dpp v142, v244 row_ror:8 row_mask:0xf bank_mask:0x3
	v_mov_b32_dpp v143, v245 row_ror:8 row_mask:0xf bank_mask:0x3
	v_mov_b32_dpp v144, v246 row_ror:8 row_mask:0xf bank_mask:0x3
	v_mov_b32_dpp v145, v247 row_ror:8 row_mask:0xf bank_mask:0x3
	v_pk_add_f32 v[60:61], v[60:61], v[138:139]
	v_pk_add_f32 v[62:63], v[62:63], v[140:141]
	v_pk_add_f32 v[56:57], v[56:57], v[142:143]
	v_pk_add_f32 v[58:59], v[58:59], v[144:145]
	v_mul_f32_e32 v235, v60, v60
	v_fmac_f32_e32 v235, v61, v61
	v_fmac_f32_e32 v235, v62, v62
	v_fmac_f32_e32 v235, v63, v63
	v_fmac_f32_e32 v235, v56, v56
	v_fmac_f32_e32 v235, v57, v57
	v_fmac_f32_e32 v235, v58, v58
	v_fmac_f32_e32 v235, v59, v59
	v_cvt_pk_bf16_f32 v138, v60, v61
	v_cvt_pk_bf16_f32 v139, v62, v63
	v_cvt_pk_bf16_f32 v140, v56, v57
	v_cvt_pk_bf16_f32 v141, v58, v59
	v_add_u32_e32 v234, 0x40000, v187
	global_store_dwordx4 v234, v[138:141], s[26:27]
	v_mov_b32_e32 v244, v56
	v_mov_b32_e32 v245, v57
	v_mov_b32_e32 v246, v58
	v_mov_b32_e32 v247, v59
	v_mov_b32_dpp v56, v60 row_ror:8 row_mask:0xf bank_mask:0x3
	v_mov_b32_dpp v57, v61 row_ror:8 row_mask:0xf bank_mask:0x3
	v_mov_b32_dpp v58, v62 row_ror:8 row_mask:0xf bank_mask:0x3
	v_mov_b32_dpp v59, v63 row_ror:8 row_mask:0xf bank_mask:0x3
	v_mov_b32_dpp v60, v244 row_ror:8 row_mask:0xf bank_mask:0xc
	v_mov_b32_dpp v61, v245 row_ror:8 row_mask:0xf bank_mask:0xc
	v_mov_b32_dpp v62, v246 row_ror:8 row_mask:0xf bank_mask:0xc
	v_mov_b32_dpp v63, v247 row_ror:8 row_mask:0xf bank_mask:0xc
	v_add_u32_e32 v230, 0x80000, v186
	v_add_u32_e32 v231, 0x88000, v186
	global_store_dwordx4 v230, v[60:63], s[24:25]
	global_store_dwordx4 v231, v[56:59], s[24:25]
	v_mov_b32_e32 v244, v150
	v_mov_b32_e32 v245, v151
	v_mov_b32_e32 v246, v152
	v_mov_b32_e32 v247, v153
	v_mov_b32_dpp v150, v154 row_ror:8 row_mask:0xf bank_mask:0xc
	v_mov_b32_dpp v151, v155 row_ror:8 row_mask:0xf bank_mask:0xc
	v_mov_b32_dpp v152, v156 row_ror:8 row_mask:0xf bank_mask:0xc
	v_mov_b32_dpp v153, v157 row_ror:8 row_mask:0xf bank_mask:0xc
	v_mov_b32_dpp v154, v244 row_ror:8 row_mask:0xf bank_mask:0x3
	v_mov_b32_dpp v155, v245 row_ror:8 row_mask:0xf bank_mask:0x3
	v_mov_b32_dpp v156, v246 row_ror:8 row_mask:0xf bank_mask:0x3
	v_mov_b32_dpp v157, v247 row_ror:8 row_mask:0xf bank_mask:0x3
	v_pk_add_f32 v[52:53], v[52:53], v[150:151]
	v_pk_add_f32 v[54:55], v[54:55], v[152:153]
	v_pk_add_f32 v[48:49], v[48:49], v[154:155]
	v_pk_add_f32 v[50:51], v[50:51], v[156:157]
	v_fmac_f32_e32 v235, v52, v52
	v_fmac_f32_e32 v235, v53, v53
	v_fmac_f32_e32 v235, v54, v54
	v_fmac_f32_e32 v235, v55, v55
	v_fmac_f32_e32 v235, v48, v48
	v_fmac_f32_e32 v235, v49, v49
	v_fmac_f32_e32 v235, v50, v50
	v_fmac_f32_e32 v235, v51, v51
	v_cvt_pk_bf16_f32 v150, v52, v53
	v_cvt_pk_bf16_f32 v151, v54, v55
	v_cvt_pk_bf16_f32 v152, v48, v49
	v_cvt_pk_bf16_f32 v153, v50, v51
	global_store_dwordx4 v234, v[150:153], s[26:27] offset:256
	v_mov_b32_e32 v244, v48
	v_mov_b32_e32 v245, v49
	v_mov_b32_e32 v246, v50
	v_mov_b32_e32 v247, v51
	v_mov_b32_dpp v48, v52 row_ror:8 row_mask:0xf bank_mask:0x3
	v_mov_b32_dpp v49, v53 row_ror:8 row_mask:0xf bank_mask:0x3
	v_mov_b32_dpp v50, v54 row_ror:8 row_mask:0xf bank_mask:0x3
	v_mov_b32_dpp v51, v55 row_ror:8 row_mask:0xf bank_mask:0x3
	v_mov_b32_dpp v52, v244 row_ror:8 row_mask:0xf bank_mask:0xc
	v_mov_b32_dpp v53, v245 row_ror:8 row_mask:0xf bank_mask:0xc
	v_mov_b32_dpp v54, v246 row_ror:8 row_mask:0xf bank_mask:0xc
; #define EPI_COL(u) (EPI_CB(u) + 8 * fq)
; DI u32x4 pack8(const float* v) { u32x4 w; w.x = pk2(v[0], v[1]); w.y = pk2(v[2], v[3]); w.z = pk2(v[4], v[5]); w.w = pk2(v[6], v[7]); return w; }
;     DI void operator()(const Acc& acc, const Unit& u, int wr, int wc, int fr, int fq) const {
;     ...
;                 const int row = EPI_ROW(u); float part = 0.f;
; #pragma unroll
;                 for (int bj = 0; bj < 2; ++bj) {
;                     const int col = EPI_COL(u);
;                     const float* rp = res + (size_t)row * 1024 + col; float* op = out + (size_t)row * 1024 + col;
;                     const f32x4 o0 = *(const f32x4*)rp + acc[ai][bj][m][0], o1 = *(const f32x4*)(rp + 4) + acc[ai][bj][m][1];
;                     *(f32x4*)op = o0; *(f32x4*)(op + 4) = o1;
;                     part += o0[0] * o0[0] + o0[1] * o0[1] + o0[2] * o0[2] + o0[3] * o0[3] + o1[0] * o1[0] + o1[1] * o1[1] + o1[2] * o1[2] + o1[3] * o1[3];
;                     const float v[8] = {o0[0], o0[1], o0[2], o0[3], o1[0], o1[1], o1[2], o1[3]};
;                     *(u32x4*)(xb + (size_t)row * 1024 + col) = pack8(v);
;                 }
	v_mov_b32_dpp v55, v247 row_ror:8 row_mask:0xf bank_mask:0xc
	global_store_dwordx4 v230, v[52:55], s[24:25] offset:512
	global_store_dwordx4 v231, v[48:51], s[24:25] offset:512
	v_mov_b32_e32 v244, v158
	v_mov_b32_e32 v245, v159
	v_mov_b32_e32 v246, v160
	v_mov_b32_e32 v247, v161
	v_mov_b32_dpp v158, v162 row_ror:8 row_mask:0xf bank_mask:0xc
	v_mov_b32_dpp v159, v163 row_ror:8 row_mask:0xf bank_mask:0xc
	v_mov_b32_dpp v160, v164 row_ror:8 row_mask:0xf bank_mask:0xc
	v_mov_b32_dpp v161, v165 row_ror:8 row_mask:0xf bank_mask:0xc
	v_mov_b32_dpp v162, v244 row_ror:8 row_mask:0xf bank_mask:0x3
	v_mov_b32_dpp v163, v245 row_ror:8 row_mask:0xf bank_mask:0x3
	v_mov_b32_dpp v164, v246 row_ror:8 row_mask:0xf bank_mask:0x3
	v_mov_b32_dpp v165, v247 row_ror:8 row_mask:0xf bank_mask:0x3
	v_pk_add_f32 v[44:45], v[44:45], v[158:159]
	v_pk_add_f32 v[46:47], v[46:47], v[160:161]
	v_pk_add_f32 v[40:41], v[40:41], v[162:163]
	v_pk_add_f32 v[42:43], v[42:43], v[164:165]
	v_mul_f32_e32 v236, v44, v44
	v_fmac_f32_e32 v236, v45, v45
	v_fmac_f32_e32 v236, v46, v46
	v_fmac_f32_e32 v236, v47, v47
	v_fmac_f32_e32 v236, v40, v40
	v_fmac_f32_e32 v236, v41, v41
	v_fmac_f32_e32 v236, v42, v42
	v_fmac_f32_e32 v236, v43, v43
	v_cvt_pk_bf16_f32 v158, v44, v45
	v_cvt_pk_bf16_f32 v159, v46, v47
	v_cvt_pk_bf16_f32 v160, v40, v41
	v_cvt_pk_bf16_f32 v161, v42, v43
	v_add_u32_e32 v234, 0x48000, v187
	global_store_dwordx4 v234, v[158:161], s[26:27]
	v_mov_b32_e32 v244, v40
	v_mov_b32_e32 v245, v41
	v_mov_b32_e32 v246, v42
	v_mov_b32_e32 v247, v43
	v_mov_b32_dpp v40, v44 row_ror:8 row_mask:0xf bank_mask:0x3
	v_mov_b32_dpp v41, v45 row_ror:8 row_mask:0xf bank_mask:0x3
	v_mov_b32_dpp v42, v46 row_ror:8 row_mask:0xf bank_mask:0x3
	v_mov_b32_dpp v43, v47 row_ror:8 row_mask:0xf bank_mask:0x3
	v_mov_b32_dpp v44, v244 row_ror:8 row_mask:0xf bank_mask:0xc
	v_mov_b32_dpp v45, v245 row_ror:8 row_mask:0xf bank_mask:0xc
	v_mov_b32_dpp v46, v246 row_ror:8 row_mask:0xf bank_mask:0xc
	v_mov_b32_dpp v47, v247 row_ror:8 row_mask:0xf bank_mask:0xc
	v_add_u32_e32 v230, 0x90000, v186
	v_add_u32_e32 v231, 0x98000, v186
	global_store_dwordx4 v230, v[44:47], s[24:25]
	global_store_dwordx4 v231, v[40:43], s[24:25]
	v_mov_b32_e32 v244, v166
	v_mov_b32_e32 v245, v167
	v_mov_b32_e32 v246, v168
	v_mov_b32_e32 v247, v169
	v_mov_b32_dpp v166, v170 row_ror:8 row_mask:0xf bank_mask:0xc
	v_mov_b32_dpp v167, v171 row_ror:8 row_mask:0xf bank_mask:0xc
	v_mov_b32_dpp v168, v172 row_ror:8 row_mask:0xf bank_mask:0xc
	v_mov_b32_dpp v169, v173 row_ror:8 row_mask:0xf bank_mask:0xc
	v_mov_b32_dpp v170, v244 row_ror:8 row_mask:0xf bank_mask:0x3
	v_mov_b32_dpp v171, v245 row_ror:8 row_mask:0xf bank_mask:0x3
	v_mov_b32_dpp v172, v246 row_ror:8 row_mask:0xf bank_mask:0x3
	v_mov_b32_dpp v173, v247 row_ror:8 row_mask:0xf bank_mask:0x3
	v_pk_add_f32 v[36:37], v[36:37], v[166:167]
	v_pk_add_f32 v[38:39], v[38:39], v[168:169]
	v_pk_add_f32 v[32:33], v[32:33], v[170:171]
	v_pk_add_f32 v[34:35], v[34:35], v[172:173]
	v_fmac_f32_e32 v236, v36, v36
	v_fmac_f32_e32 v236, v37, v37
	v_fmac_f32_e32 v236, v38, v38
	v_fmac_f32_e32 v236, v39, v39
	v_fmac_f32_e32 v236, v32, v32
	v_fmac_f32_e32 v236, v33, v33
	v_fmac_f32_e32 v236, v34, v34
	v_fmac_f32_e32 v236, v35, v35
	v_cvt_pk_bf16_f32 v166, v36, v37
	v_cvt_pk_bf16_f32 v167, v38, v39
	v_cvt_pk_bf16_f32 v168, v32, v33
	v_cvt_pk_bf16_f32 v169, v34, v35
	global_store_dwordx4 v234, v[166:169], s[26:27] offset:256
	v_mov_b32_e32 v244, v32
	v_mov_b32_e32 v245, v33
	v_mov_b32_e32 v246, v34
	v_mov_b32_e32 v247, v35
	v_mov_b32_dpp v32, v36 row_ror:8 row_mask:0xf bank_mask:0x3
	v_mov_b32_dpp v33, v37 row_ror:8 row_mask:0xf bank_mask:0x3
	v_mov_b32_dpp v34, v38 row_ror:8 row_mask:0xf bank_mask:0x3
	v_mov_b32_dpp v35, v39 row_ror:8 row_mask:0xf bank_mask:0x3
	v_mov_b32_dpp v36, v244 row_ror:8 row_mask:0xf bank_mask:0xc
	v_mov_b32_dpp v37, v245 row_ror:8 row_mask:0xf bank_mask:0xc
	v_mov_b32_dpp v38, v246 row_ror:8 row_mask:0xf bank_mask:0xc
	v_mov_b32_dpp v39, v247 row_ror:8 row_mask:0xf bank_mask:0xc
	global_store_dwordx4 v230, v[36:39], s[24:25] offset:512
	global_store_dwordx4 v231, v[32:35], s[24:25] offset:512
	v_mov_b32_e32 v244, v174
	v_mov_b32_e32 v245, v175
	v_mov_b32_e32 v246, v176
	v_mov_b32_e32 v247, v177
	v_mov_b32_dpp v174, v178 row_ror:8 row_mask:0xf bank_mask:0xc
	v_mov_b32_dpp v175, v179 row_ror:8 row_mask:0xf bank_mask:0xc
	v_mov_b32_dpp v176, v180 row_ror:8 row_mask:0xf bank_mask:0xc
	v_mov_b32_dpp v177, v181 row_ror:8 row_mask:0xf bank_mask:0xc
	v_mov_b32_dpp v178, v244 row_ror:8 row_mask:0xf bank_mask:0x3
	v_mov_b32_dpp v179, v245 row_ror:8 row_mask:0xf bank_mask:0x3
	v_mov_b32_dpp v180, v246 row_ror:8 row_mask:0xf bank_mask:0x3
	v_mov_b32_dpp v181, v247 row_ror:8 row_mask:0xf bank_mask:0x3
	v_pk_add_f32 v[28:29], v[28:29], v[174:175]
	v_pk_add_f32 v[30:31], v[30:31], v[176:177]
	v_pk_add_f32 v[24:25], v[24:25], v[178:179]
	v_pk_add_f32 v[26:27], v[26:27], v[180:181]
	v_mul_f32_e32 v237, v28, v28
	v_fmac_f32_e32 v237, v29, v29
	v_fmac_f32_e32 v237, v30, v30
	v_fmac_f32_e32 v237, v31, v31
	v_fmac_f32_e32 v237, v24, v24
	v_fmac_f32_e32 v237, v25, v25
	v_fmac_f32_e32 v237, v26, v26
	v_fmac_f32_e32 v237, v27, v27
	v_cvt_pk_bf16_f32 v174, v28, v29
	v_cvt_pk_bf16_f32 v175, v30, v31
	v_cvt_pk_bf16_f32 v176, v24, v25
	v_cvt_pk_bf16_f32 v177, v26, v27
	v_add_u32_e32 v234, 0x50000, v187
	global_store_dwordx4 v234, v[174:177], s[26:27]
	v_mov_b32_e32 v244, v24
	v_mov_b32_e32 v245, v25
	v_mov_b32_e32 v246, v26
	v_mov_b32_e32 v247, v27
	v_mov_b32_dpp v24, v28 row_ror:8 row_mask:0xf bank_mask:0x3
	v_mov_b32_dpp v25, v29 row_ror:8 row_mask:0xf bank_mask:0x3
	v_mov_b32_dpp v26, v30 row_ror:8 row_mask:0xf bank_mask:0x3
; #define EPI_COL(u) (EPI_CB(u) + 8 * fq)
; DI u32x4 pack8(const float* v) { u32x4 w; w.x = pk2(v[0], v[1]); w.y = pk2(v[2], v[3]); w.z = pk2(v[4], v[5]); w.w = pk2(v[6], v[7]); return w; }
;     DI void operator()(const Acc& acc, const Unit& u, int wr, int wc, int fr, int fq) const {
;     ...
;                 const int row = EPI_ROW(u); float part = 0.f;
; #pragma unroll
;                 for (int bj = 0; bj < 2; ++bj) {
;                     const int col = EPI_COL(u);
;                     const float* rp = res + (size_t)row * 1024 + col; float* op = out + (size_t)row * 1024 + col;
;                     const f32x4 o0 = *(const f32x4*)rp + acc[ai][bj][m][0], o1 = *(const f32x4*)(rp + 4) + acc[ai][bj][m][1];
;                     *(f32x4*)op = o0; *(f32x4*)(op + 4) = o1;
;                     part += o0[0] * o0[0] + o0[1] * o0[1] + o0[2] * o0[2] + o0[3] * o0[3] + o1[0] * o1[0] + o1[1] * o1[1] + o1[2] * o1[2] + o1[3] * o1[3];
;                     const float v[8] = {o0[0], o0[1], o0[2], o0[3], o1[0], o1[1], o1[2], o1[3]};
;                     *(u32x4*)(xb + (size_t)row * 1024 + col) = pack8(v);
;                 }
;                 part += __shfl_xor(part, 16); part += __shfl_xor(part, 32);
	v_mov_b32_dpp v27, v31 row_ror:8 row_mask:0xf bank_mask:0x3
	v_mov_b32_dpp v28, v244 row_ror:8 row_mask:0xf bank_mask:0xc
	v_mov_b32_dpp v29, v245 row_ror:8 row_mask:0xf bank_mask:0xc
	v_mov_b32_dpp v30, v246 row_ror:8 row_mask:0xf bank_mask:0xc
	v_mov_b32_dpp v31, v247 row_ror:8 row_mask:0xf bank_mask:0xc
	v_add_u32_e32 v230, 0xa0000, v186
	v_add_u32_e32 v231, 0xa8000, v186
	global_store_dwordx4 v230, v[28:31], s[24:25]
	global_store_dwordx4 v231, v[24:27], s[24:25]
	v_mov_b32_e32 v244, v182
	v_mov_b32_e32 v245, v183
	v_mov_b32_e32 v246, v184
	v_mov_b32_e32 v247, v185
	v_mov_b32_dpp v182, v210 row_ror:8 row_mask:0xf bank_mask:0xc
	v_mov_b32_dpp v183, v211 row_ror:8 row_mask:0xf bank_mask:0xc
	v_mov_b32_dpp v184, v212 row_ror:8 row_mask:0xf bank_mask:0xc
	v_mov_b32_dpp v185, v213 row_ror:8 row_mask:0xf bank_mask:0xc
	v_mov_b32_dpp v210, v244 row_ror:8 row_mask:0xf bank_mask:0x3
	v_mov_b32_dpp v211, v245 row_ror:8 row_mask:0xf bank_mask:0x3
	v_mov_b32_dpp v212, v246 row_ror:8 row_mask:0xf bank_mask:0x3
	v_mov_b32_dpp v213, v247 row_ror:8 row_mask:0xf bank_mask:0x3
	v_pk_add_f32 v[20:21], v[20:21], v[182:183]
	v_pk_add_f32 v[22:23], v[22:23], v[184:185]
	v_pk_add_f32 v[16:17], v[16:17], v[210:211]
	v_pk_add_f32 v[18:19], v[18:19], v[212:213]
	v_fmac_f32_e32 v237, v20, v20
	v_fmac_f32_e32 v237, v21, v21
	v_fmac_f32_e32 v237, v22, v22
	v_fmac_f32_e32 v237, v23, v23
	v_fmac_f32_e32 v237, v16, v16
	v_fmac_f32_e32 v237, v17, v17
	v_fmac_f32_e32 v237, v18, v18
	v_fmac_f32_e32 v237, v19, v19
	v_cvt_pk_bf16_f32 v182, v20, v21
	v_cvt_pk_bf16_f32 v183, v22, v23
	v_cvt_pk_bf16_f32 v184, v16, v17
	v_cvt_pk_bf16_f32 v185, v18, v19
	global_store_dwordx4 v234, v[182:185], s[26:27] offset:256
	v_mov_b32_e32 v244, v16
	v_mov_b32_e32 v245, v17
	v_mov_b32_e32 v246, v18
	v_mov_b32_e32 v247, v19
	v_mov_b32_dpp v16, v20 row_ror:8 row_mask:0xf bank_mask:0x3
	v_mov_b32_dpp v17, v21 row_ror:8 row_mask:0xf bank_mask:0x3
	v_mov_b32_dpp v18, v22 row_ror:8 row_mask:0xf bank_mask:0x3
	v_mov_b32_dpp v19, v23 row_ror:8 row_mask:0xf bank_mask:0x3
	v_mov_b32_dpp v20, v244 row_ror:8 row_mask:0xf bank_mask:0xc
	v_mov_b32_dpp v21, v245 row_ror:8 row_mask:0xf bank_mask:0xc
	v_mov_b32_dpp v22, v246 row_ror:8 row_mask:0xf bank_mask:0xc
	v_mov_b32_dpp v23, v247 row_ror:8 row_mask:0xf bank_mask:0xc
	global_store_dwordx4 v230, v[20:23], s[24:25] offset:512
	global_store_dwordx4 v231, v[16:19], s[24:25] offset:512
	v_mov_b32_e32 v244, v214
	v_mov_b32_e32 v245, v215
	v_mov_b32_e32 v246, v216
	v_mov_b32_e32 v247, v217
	v_mov_b32_dpp v214, v218 row_ror:8 row_mask:0xf bank_mask:0xc
	v_mov_b32_dpp v215, v219 row_ror:8 row_mask:0xf bank_mask:0xc
	v_mov_b32_dpp v216, v220 row_ror:8 row_mask:0xf bank_mask:0xc
	v_mov_b32_dpp v217, v221 row_ror:8 row_mask:0xf bank_mask:0xc
	v_mov_b32_dpp v218, v244 row_ror:8 row_mask:0xf bank_mask:0x3
	v_mov_b32_dpp v219, v245 row_ror:8 row_mask:0xf bank_mask:0x3
	v_mov_b32_dpp v220, v246 row_ror:8 row_mask:0xf bank_mask:0x3
	v_mov_b32_dpp v221, v247 row_ror:8 row_mask:0xf bank_mask:0x3
	v_pk_add_f32 v[12:13], v[12:13], v[214:215]
	v_pk_add_f32 v[14:15], v[14:15], v[216:217]
	v_pk_add_f32 v[8:9], v[8:9], v[218:219]
	v_pk_add_f32 v[10:11], v[10:11], v[220:221]
	v_mul_f32_e32 v248, v12, v12
	v_fmac_f32_e32 v248, v13, v13
	v_fmac_f32_e32 v248, v14, v14
	v_fmac_f32_e32 v248, v15, v15
	v_fmac_f32_e32 v248, v8, v8
	v_fmac_f32_e32 v248, v9, v9
	v_fmac_f32_e32 v248, v10, v10
	v_fmac_f32_e32 v248, v11, v11
	v_cvt_pk_bf16_f32 v214, v12, v13
	v_cvt_pk_bf16_f32 v215, v14, v15
	v_cvt_pk_bf16_f32 v216, v8, v9
	v_cvt_pk_bf16_f32 v217, v10, v11
	v_add_u32_e32 v234, 0x58000, v187
	global_store_dwordx4 v234, v[214:217], s[26:27]
	v_mov_b32_e32 v244, v8
	v_mov_b32_e32 v245, v9
	v_mov_b32_e32 v246, v10
	v_mov_b32_e32 v247, v11
	v_mov_b32_dpp v8, v12 row_ror:8 row_mask:0xf bank_mask:0x3
	v_mov_b32_dpp v9, v13 row_ror:8 row_mask:0xf bank_mask:0x3
	v_mov_b32_dpp v10, v14 row_ror:8 row_mask:0xf bank_mask:0x3
	v_mov_b32_dpp v11, v15 row_ror:8 row_mask:0xf bank_mask:0x3
	v_mov_b32_dpp v12, v244 row_ror:8 row_mask:0xf bank_mask:0xc
	v_mov_b32_dpp v13, v245 row_ror:8 row_mask:0xf bank_mask:0xc
	v_mov_b32_dpp v14, v246 row_ror:8 row_mask:0xf bank_mask:0xc
	v_mov_b32_dpp v15, v247 row_ror:8 row_mask:0xf bank_mask:0xc
	v_add_u32_e32 v230, 0xb0000, v186
	v_add_u32_e32 v231, 0xb8000, v186
	global_store_dwordx4 v230, v[12:15], s[24:25]
	global_store_dwordx4 v231, v[8:11], s[24:25]
	v_mov_b32_e32 v244, v222
	v_mov_b32_e32 v245, v223
	v_mov_b32_e32 v246, v224
	v_mov_b32_e32 v247, v225
	v_mov_b32_dpp v222, v226 row_ror:8 row_mask:0xf bank_mask:0xc
	v_mov_b32_dpp v223, v227 row_ror:8 row_mask:0xf bank_mask:0xc
	v_mov_b32_dpp v224, v228 row_ror:8 row_mask:0xf bank_mask:0xc
	v_mov_b32_dpp v225, v229 row_ror:8 row_mask:0xf bank_mask:0xc
	v_mov_b32_dpp v226, v244 row_ror:8 row_mask:0xf bank_mask:0x3
	v_mov_b32_dpp v227, v245 row_ror:8 row_mask:0xf bank_mask:0x3
	v_mov_b32_dpp v228, v246 row_ror:8 row_mask:0xf bank_mask:0x3
	v_mov_b32_dpp v229, v247 row_ror:8 row_mask:0xf bank_mask:0x3
	v_pk_add_f32 v[4:5], v[4:5], v[222:223]
	v_pk_add_f32 v[6:7], v[6:7], v[224:225]
	v_pk_add_f32 v[0:1], v[0:1], v[226:227]
	v_pk_add_f32 v[2:3], v[2:3], v[228:229]
	v_fmac_f32_e32 v248, v4, v4
	v_fmac_f32_e32 v248, v5, v5
	v_fmac_f32_e32 v248, v6, v6
	v_fmac_f32_e32 v248, v7, v7
	v_fmac_f32_e32 v248, v0, v0
	v_fmac_f32_e32 v248, v1, v1
	v_fmac_f32_e32 v248, v2, v2
	v_fmac_f32_e32 v248, v3, v3
	v_cvt_pk_bf16_f32 v222, v4, v5
	v_cvt_pk_bf16_f32 v223, v6, v7
	v_cvt_pk_bf16_f32 v224, v0, v1
	v_cvt_pk_bf16_f32 v225, v2, v3
	global_store_dwordx4 v234, v[222:225], s[26:27] offset:256
	v_mov_b32_e32 v244, v0
	v_mov_b32_e32 v245, v1
	v_mov_b32_e32 v246, v2
	v_mov_b32_e32 v247, v3
	v_mov_b32_dpp v0, v4 row_ror:8 row_mask:0xf bank_mask:0x3
	v_mov_b32_dpp v1, v5 row_ror:8 row_mask:0xf bank_mask:0x3
	v_mov_b32_dpp v2, v6 row_ror:8 row_mask:0xf bank_mask:0x3
	v_mov_b32_dpp v3, v7 row_ror:8 row_mask:0xf bank_mask:0x3
	v_mov_b32_dpp v4, v244 row_ror:8 row_mask:0xf bank_mask:0xc
	v_mov_b32_dpp v5, v245 row_ror:8 row_mask:0xf bank_mask:0xc
	v_mov_b32_dpp v6, v246 row_ror:8 row_mask:0xf bank_mask:0xc
	v_mov_b32_dpp v7, v247 row_ror:8 row_mask:0xf bank_mask:0xc
	global_store_dwordx4 v230, v[4:7], s[24:25] offset:512
	global_store_dwordx4 v231, v[0:3], s[24:25] offset:512
	ds_bpermute_b32 v138, v242, v235
	ds_bpermute_b32 v142, v242, v236
	ds_bpermute_b32 v150, v242, v237
	ds_bpermute_b32 v154, v242, v248
	s_waitcnt lgkmcnt(0)
;     DI void operator()(const Acc& acc, const Unit& u, int wr, int wc, int fr, int fq) const {
;     ...
;                 part += __shfl_xor(part, 16); part += __shfl_xor(part, 32);
;                 if (fq == 0) atomicAdd(rss + row, part);
;             }
	v_add_f32_e32 v235, v235, v138
	v_add_f32_e32 v236, v236, v142
	v_add_f32_e32 v237, v237, v150
	v_add_f32_e32 v248, v248, v154
	ds_bpermute_b32 v138, v243, v235
	ds_bpermute_b32 v142, v243, v236
	ds_bpermute_b32 v150, v243, v237
	ds_bpermute_b32 v154, v243, v248
	s_waitcnt lgkmcnt(0)
	v_add_f32_e32 v235, v235, v138
	v_add_f32_e32 v236, v236, v142
	v_add_f32_e32 v237, v237, v150
	v_add_f32_e32 v248, v248, v154
	s_and_saveexec_b64 s[6:7], vcc
	v_lshlrev_b32_e32 v234, 2, v240
	global_atomic_add_f32 v234, v235, s[38:39] offset:512
	global_atomic_add_f32 v234, v236, s[38:39] offset:576
	global_atomic_add_f32 v234, v237, s[38:39] offset:640
	global_atomic_add_f32 v234, v248, s[38:39] offset:704
	s_or_b64 exec, exec, s[6:7]
	s_mov_b64 s[6:7], exec
